# P3 epilogue x loads without nt (y stores plain)
# baseline (speedup 1.0000x reference)
.LBB0_502:
	s_lshl_b32 s0, s14, 8
	s_add_i32 s4, s0, s15
	s_lshl_b32 s1, s3, 5
	v_or_b32_e32 v130, s4, v233
	s_lshl_b32 s4, s51, 8
	s_or_b32 s1, s4, s1
	v_ashrrev_i32_e32 v131, 31, v130
	v_lshl_or_b32 v128, v144, 2, s1
	v_lshlrev_b64 v[132:133], 12, v[130:131]
	v_ashrrev_i32_e32 v129, 31, v128
	v_lshl_add_u64 v[134:135], s[44:45], 0, v[132:133]
	v_lshl_add_u64 v[142:143], v[128:129], 2, v[134:135]
	s_barrier
	v_lshl_add_u32 v198, v128, 2, v132
	global_load_dwordx4 v[182:185], v198, s[44:45]
	global_load_dwordx4 v[186:189], v198, s[44:45] offset:64
	global_load_dwordx4 v[190:193], v198, s[44:45] offset:512
	global_load_dwordx4 v[194:197], v198, s[44:45] offset:576
	v_add_u32_e32 v199, 0x10000, v198
	global_load_dwordx4 v[202:205], v199, s[44:45]
	global_load_dwordx4 v[206:209], v199, s[44:45] offset:64
	global_load_dwordx4 v[210:213], v199, s[44:45] offset:512
	global_load_dwordx4 v[214:217], v199, s[44:45] offset:576
	v_add_u32_e32 v199, 0x20000, v198
	global_load_dwordx4 v[218:221], v199, s[44:45]
	global_load_dwordx4 v[222:225], v199, s[44:45] offset:64
	global_load_dwordx4 v[234:237], v199, s[44:45] offset:512
	global_load_dwordx4 v[238:241], v199, s[44:45] offset:576
	v_mbcnt_lo_u32_b32 v142, -1, 0
	v_mbcnt_hi_u32_b32 v142, -1, v142
	v_and_b32_e32 v145, 64, v142
	v_xor_b32_e32 v143, 16, v142
	v_add_u32_e32 v145, 64, v145
	v_cmp_lt_i32_e32 vcc, v143, v145
	v_xor_b32_e32 v154, 32, v142
	s_lshl_b32 s1, s15, 2
	v_cndmask_b32_e32 v143, v142, v143, vcc
	v_lshlrev_b32_e32 v171, 2, v143
	v_cmp_lt_i32_e32 vcc, v154, v145
	s_add_i32 s1, s1, 0
	s_lshl_b32 s3, s3, 10
	s_add_i32 s1, s1, s3
	v_lshl_add_u32 v173, v233, 2, s1
	s_waitcnt vmcnt(8)
	v_pk_add_f32 v[126:127], v[126:127], v[184:185]
	v_pk_add_f32 v[124:125], v[124:125], v[182:183]
	v_pk_add_f32 v[122:123], v[122:123], v[188:189]
	v_pk_add_f32 v[120:121], v[120:121], v[186:187]
	v_pk_add_f32 v[118:119], v[118:119], v[192:193]
	v_pk_add_f32 v[116:117], v[116:117], v[190:191]
	v_mul_f32_e32 v134, v125, v125
	v_mul_f32_e32 v135, v127, v127
	v_mul_f32_e32 v136, v121, v121
	v_mul_f32_e32 v137, v123, v123
	v_pk_add_f32 v[114:115], v[114:115], v[196:197]
	v_pk_add_f32 v[112:113], v[112:113], v[194:195]
	v_add_u32_e32 v199, 0x30000, v198
	global_load_dwordx4 v[182:185], v199, s[44:45]
	global_load_dwordx4 v[186:189], v199, s[44:45] offset:64
	global_load_dwordx4 v[190:193], v199, s[44:45] offset:512
	global_load_dwordx4 v[194:197], v199, s[44:45] offset:576
	v_mul_f32_e32 v138, v117, v117
	v_mul_f32_e32 v139, v119, v119
	v_fmac_f32_e32 v134, v124, v124
	v_fmac_f32_e32 v135, v126, v126
	v_fmac_f32_e32 v136, v120, v120
	v_fmac_f32_e32 v137, v122, v122
	v_mul_f32_e32 v140, v113, v113
	v_mul_f32_e32 v141, v115, v115
	v_fmac_f32_e32 v138, v116, v116
	v_fmac_f32_e32 v139, v118, v118
	v_add_f32_e32 v134, v134, v135
	v_add_f32_e32 v135, v136, v137
	v_fmac_f32_e32 v140, v112, v112
	v_fmac_f32_e32 v141, v114, v114
	v_add_f32_e32 v136, v138, v139
	v_add_f32_e32 v134, v134, v135
	v_add_f32_e32 v137, v140, v141
	v_add_f32_e32 v134, v134, v136
	v_add_f32_e32 v134, v134, v137
	ds_bpermute_b32 v135, v171, v134
	v_cndmask_b32_e32 v136, v142, v154, vcc
	v_lshlrev_b32_e32 v172, 2, v136
	v_cmp_eq_u32_e32 vcc, 0, v144
	s_waitcnt lgkmcnt(0)
	v_add_f32_e32 v134, v134, v135
	ds_bpermute_b32 v135, v172, v134
	s_and_saveexec_b64 s[4:5], vcc
	s_cbranch_execz .LBB0_504
	s_waitcnt lgkmcnt(0)
	v_add_f32_e32 v134, v134, v135
	ds_write_b32 v173, v134
.LBB0_504:
	s_or_b64 exec, exec, s[4:5]
	v_or_b32_e32 v136, 16, v130
	v_ashrrev_i32_e32 v137, 31, v136
	s_waitcnt lgkmcnt(0)
	v_lshlrev_b64 v[134:135], 12, v[136:137]
	v_lshl_add_u64 v[138:139], s[44:45], 0, v[134:135]
	v_lshl_add_u64 v[150:151], v[128:129], 2, v[138:139]
	s_nop 0
	s_waitcnt vmcnt(11)
	v_pk_add_f32 v[110:111], v[110:111], v[204:205]
	v_pk_add_f32 v[108:109], v[108:109], v[202:203]
	s_waitcnt vmcnt(10)
	v_pk_add_f32 v[106:107], v[106:107], v[208:209]
	v_pk_add_f32 v[104:105], v[104:105], v[206:207]
	s_waitcnt vmcnt(9)
	v_pk_add_f32 v[102:103], v[102:103], v[212:213]
	v_pk_add_f32 v[100:101], v[100:101], v[210:211]
	v_mul_f32_e32 v138, v109, v109
	v_mul_f32_e32 v139, v111, v111
	v_mul_f32_e32 v140, v105, v105
	v_mul_f32_e32 v141, v107, v107
	s_waitcnt vmcnt(8)
	v_pk_add_f32 v[98:99], v[98:99], v[216:217]
	v_pk_add_f32 v[96:97], v[96:97], v[214:215]
	v_add_u32_e32 v199, 0x80000, v198
	global_load_dwordx4 v[202:205], v199, s[44:45]
	global_load_dwordx4 v[206:209], v199, s[44:45] offset:64
	global_load_dwordx4 v[210:213], v199, s[44:45] offset:512
	global_load_dwordx4 v[214:217], v199, s[44:45] offset:576
	v_mul_f32_e32 v142, v101, v101
	v_mul_f32_e32 v143, v103, v103
	v_fmac_f32_e32 v138, v108, v108
	v_fmac_f32_e32 v139, v110, v110
	v_fmac_f32_e32 v140, v104, v104
	v_fmac_f32_e32 v141, v106, v106
	v_mul_f32_e32 v144, v97, v97
	v_mul_f32_e32 v145, v99, v99
	v_fmac_f32_e32 v142, v100, v100
	v_fmac_f32_e32 v143, v102, v102
	v_add_f32_e32 v138, v138, v139
	v_add_f32_e32 v139, v140, v141
	v_fmac_f32_e32 v144, v96, v96
	v_fmac_f32_e32 v145, v98, v98
	v_add_f32_e32 v140, v142, v143
	v_add_f32_e32 v138, v138, v139
	v_add_f32_e32 v138, v138, v140
	v_add_f32_e32 v139, v144, v145
	v_add_f32_e32 v138, v138, v139
	ds_bpermute_b32 v139, v171, v138
	s_waitcnt lgkmcnt(0)
	v_add_f32_e32 v138, v138, v139
	ds_bpermute_b32 v139, v172, v138
	s_and_saveexec_b64 s[4:5], vcc
	s_cbranch_execz .LBB0_506
	s_waitcnt lgkmcnt(0)
	v_add_f32_e32 v138, v138, v139
	ds_write_b32 v173, v138 offset:64
.LBB0_506:
	s_or_b64 exec, exec, s[4:5]
	v_or_b32_e32 v140, 32, v130
	v_ashrrev_i32_e32 v141, 31, v140
	s_waitcnt lgkmcnt(0)
	v_lshlrev_b64 v[138:139], 12, v[140:141]
	v_lshl_add_u64 v[142:143], s[44:45], 0, v[138:139]
	v_lshl_add_u64 v[154:155], v[128:129], 2, v[142:143]
	s_nop 0
	s_waitcnt vmcnt(11)
	v_pk_add_f32 v[94:95], v[94:95], v[220:221]
	v_pk_add_f32 v[92:93], v[92:93], v[218:219]
	s_waitcnt vmcnt(10)
	v_pk_add_f32 v[90:91], v[90:91], v[224:225]
	v_pk_add_f32 v[88:89], v[88:89], v[222:223]
	s_waitcnt vmcnt(9)
	v_pk_add_f32 v[86:87], v[86:87], v[236:237]
	v_pk_add_f32 v[84:85], v[84:85], v[234:235]
	v_mul_f32_e32 v142, v93, v93
	v_mul_f32_e32 v143, v95, v95
	v_mul_f32_e32 v144, v89, v89
	v_mul_f32_e32 v145, v91, v91
	s_waitcnt vmcnt(8)
	v_pk_add_f32 v[82:83], v[82:83], v[240:241]
	v_pk_add_f32 v[80:81], v[80:81], v[238:239]
	v_add_u32_e32 v199, 0x90000, v198
	global_load_dwordx4 v[218:221], v199, s[44:45]
	global_load_dwordx4 v[222:225], v199, s[44:45] offset:64
	global_load_dwordx4 v[234:237], v199, s[44:45] offset:512
	global_load_dwordx4 v[238:241], v199, s[44:45] offset:576
	v_mul_f32_e32 v146, v85, v85
	v_mul_f32_e32 v147, v87, v87
	v_fmac_f32_e32 v142, v92, v92
	v_fmac_f32_e32 v143, v94, v94
	v_fmac_f32_e32 v144, v88, v88
	v_fmac_f32_e32 v145, v90, v90
	v_mul_f32_e32 v148, v81, v81
	v_mul_f32_e32 v149, v83, v83
	v_fmac_f32_e32 v146, v84, v84
	v_fmac_f32_e32 v147, v86, v86
	v_add_f32_e32 v142, v142, v143
	v_add_f32_e32 v143, v144, v145
	v_fmac_f32_e32 v148, v80, v80
	v_fmac_f32_e32 v149, v82, v82
	v_add_f32_e32 v144, v146, v147
	v_add_f32_e32 v142, v142, v143
	v_add_f32_e32 v142, v142, v144
	v_add_f32_e32 v143, v148, v149
	v_add_f32_e32 v142, v142, v143
	ds_bpermute_b32 v143, v171, v142
	s_waitcnt lgkmcnt(0)
	v_add_f32_e32 v142, v142, v143
	ds_bpermute_b32 v143, v172, v142
	s_and_saveexec_b64 s[4:5], vcc
	s_cbranch_execz .LBB0_508
	s_waitcnt lgkmcnt(0)
	v_add_f32_e32 v142, v142, v143
	ds_write_b32 v173, v142 offset:128
.LBB0_508:
	s_or_b64 exec, exec, s[4:5]
	v_or_b32_e32 v144, 48, v130
	v_ashrrev_i32_e32 v145, 31, v144
	s_waitcnt lgkmcnt(0)
	v_lshlrev_b64 v[142:143], 12, v[144:145]
	v_lshl_add_u64 v[146:147], s[44:45], 0, v[142:143]
	v_lshl_add_u64 v[158:159], v[128:129], 2, v[146:147]
	s_nop 0
	s_waitcnt vmcnt(11)
	v_pk_add_f32 v[78:79], v[78:79], v[184:185]
	v_pk_add_f32 v[146:147], v[76:77], v[182:183]
	s_waitcnt vmcnt(10)
	v_pk_add_f32 v[74:75], v[74:75], v[188:189]
	v_pk_add_f32 v[76:77], v[72:73], v[186:187]
	s_waitcnt vmcnt(9)
	v_pk_add_f32 v[70:71], v[70:71], v[192:193]
	v_pk_add_f32 v[68:69], v[68:69], v[190:191]
	v_mul_f32_e32 v72, v147, v147
	v_mul_f32_e32 v73, v79, v79
	v_mul_f32_e32 v148, v77, v77
	v_mul_f32_e32 v149, v75, v75
	s_waitcnt vmcnt(8)
	v_pk_add_f32 v[66:67], v[66:67], v[196:197]
	v_pk_add_f32 v[64:65], v[64:65], v[194:195]
	v_add_u32_e32 v199, 0xa0000, v198
	global_load_dwordx4 v[182:185], v199, s[44:45]
	global_load_dwordx4 v[186:189], v199, s[44:45] offset:64
	global_load_dwordx4 v[190:193], v199, s[44:45] offset:512
	global_load_dwordx4 v[194:197], v199, s[44:45] offset:576
	v_mul_f32_e32 v150, v69, v69
	v_mul_f32_e32 v151, v71, v71
	v_fmac_f32_e32 v72, v146, v146
	v_fmac_f32_e32 v73, v78, v78
	v_fmac_f32_e32 v148, v76, v76
	v_fmac_f32_e32 v149, v74, v74
	v_mul_f32_e32 v152, v65, v65
	v_mul_f32_e32 v153, v67, v67
	v_fmac_f32_e32 v150, v68, v68
	v_fmac_f32_e32 v151, v70, v70
	v_add_f32_e32 v72, v72, v73
	v_add_f32_e32 v73, v148, v149
	v_fmac_f32_e32 v152, v64, v64
	v_fmac_f32_e32 v153, v66, v66
	v_add_f32_e32 v148, v150, v151
	v_add_f32_e32 v72, v72, v73
	v_add_f32_e32 v72, v72, v148
	v_add_f32_e32 v73, v152, v153
	v_add_f32_e32 v72, v72, v73
	ds_bpermute_b32 v73, v171, v72
	s_waitcnt lgkmcnt(0)
	v_add_f32_e32 v72, v72, v73
	ds_bpermute_b32 v73, v172, v72
	s_and_saveexec_b64 s[4:5], vcc
	s_cbranch_execz .LBB0_510
	s_waitcnt lgkmcnt(0)
	v_add_f32_e32 v72, v72, v73
	ds_write_b32 v173, v72 offset:192
.LBB0_510:
	s_or_b64 exec, exec, s[4:5]
	s_mov_b64 s[4:5], 0x80000
	s_waitcnt lgkmcnt(0)
	v_lshl_add_u64 v[72:73], v[132:133], 0, s[4:5]
	v_lshl_add_u64 v[148:149], s[44:45], 0, v[72:73]
	v_lshl_add_u64 v[160:161], v[128:129], 2, v[148:149]
	s_nop 0
	s_waitcnt vmcnt(11)
	v_pk_add_f32 v[62:63], v[62:63], v[204:205]
	v_pk_add_f32 v[148:149], v[60:61], v[202:203]
	s_waitcnt vmcnt(10)
	v_pk_add_f32 v[58:59], v[58:59], v[208:209]
	v_pk_add_f32 v[60:61], v[56:57], v[206:207]
	s_waitcnt vmcnt(9)
	v_pk_add_f32 v[54:55], v[54:55], v[212:213]
	v_pk_add_f32 v[52:53], v[52:53], v[210:211]
	v_mul_f32_e32 v56, v149, v149
	v_mul_f32_e32 v57, v63, v63
	v_mul_f32_e32 v150, v61, v61
	v_mul_f32_e32 v151, v59, v59
	s_waitcnt vmcnt(8)
	v_pk_add_f32 v[50:51], v[50:51], v[216:217]
	v_pk_add_f32 v[48:49], v[48:49], v[214:215]
	v_add_u32_e32 v199, 0xb0000, v198
	global_load_dwordx4 v[202:205], v199, s[44:45]
	global_load_dwordx4 v[206:209], v199, s[44:45] offset:64
	global_load_dwordx4 v[210:213], v199, s[44:45] offset:512
	global_load_dwordx4 v[214:217], v199, s[44:45] offset:576
	v_mul_f32_e32 v152, v53, v53
	v_mul_f32_e32 v153, v55, v55
	v_fmac_f32_e32 v56, v148, v148
	v_fmac_f32_e32 v57, v62, v62
	v_fmac_f32_e32 v150, v60, v60
	v_fmac_f32_e32 v151, v58, v58
	v_mul_f32_e32 v154, v49, v49
	v_mul_f32_e32 v155, v51, v51
	v_fmac_f32_e32 v152, v52, v52
	v_fmac_f32_e32 v153, v54, v54
	v_add_f32_e32 v56, v56, v57
	v_add_f32_e32 v57, v150, v151
	v_fmac_f32_e32 v154, v48, v48
	v_fmac_f32_e32 v155, v50, v50
	v_add_f32_e32 v150, v152, v153
	v_add_f32_e32 v56, v56, v57
	v_add_f32_e32 v56, v56, v150
	v_add_f32_e32 v57, v154, v155
	v_add_f32_e32 v56, v56, v57
	ds_bpermute_b32 v57, v171, v56
	s_waitcnt lgkmcnt(0)
	v_add_f32_e32 v56, v56, v57
	ds_bpermute_b32 v57, v172, v56
	s_and_saveexec_b64 s[4:5], vcc
	s_cbranch_execz .LBB0_512
	s_waitcnt lgkmcnt(0)
	v_add_f32_e32 v56, v56, v57
	ds_write_b32 v173, v56 offset:512
